# phase 8 sample-row tiles split along K into 11 units each (44 CUs in the last round), partial sums combined with f32 atomics onto zero-initialised y_sample
# baseline (speedup 1.0000x reference)
;     __device__ __forceinline__ bool next(int i, Unit& u) const {
;         int L = (i / UPT) * G + c;
;         constexpr int n0 = nM0 * nN0, n1 = nM1 * nN1, n2 = nM2 * nN2;
;         if (L < n0) { tile_of(L, nM0, nN0, u.pm, u.pn); u.g = (UPT > 1) ? (i % UPT) : 0; return true; }
; template <class Epi, class Sched>
; __device__ __forceinline__ void gemm_phase(LAS unsigned char* lds, const int K, const Sched& S, const Epi& E) {
;     ...
;     Unit cur, nxt; int ui = 0;
;     if (!S.next(0, cur)) return;
.LBB0_1356:
	s_or_b64 exec, exec, s[8:9]
	s_mov_b64 s[8:9], s[86:87]
	v_mov_b32_e32 v8, v230
	s_waitcnt lgkmcnt(0)
	s_barrier
	s_cmpk_gt_u32 s2, 0x7f
	s_cbranch_scc1 .Lzs_skip
	s_load_dwordx2 s[100:101], s[86:87], 0xe0
	v_lshlrev_b32_e32 v0, 3, v230
	v_mov_b32_e32 v2, 0
	v_mov_b32_e32 v3, 0
	s_lshl_b32 s98, s2, 12
	s_waitcnt lgkmcnt(0)
	s_add_u32 s100, s100, s98
	s_addc_u32 s101, s101, 0
	s_add_u32 s100, s100, 0x10000000
	s_addc_u32 s101, s101, 0
	global_store_dwordx2 v0, v[2:3], s[100:101]
.Lzs_skip:
	s_cmpk_gt_i32 s2, 0x1615
	v_readfirstlane_b32 s0, v8
	s_cbranch_scc1 .LBB0_1376
	s_ashr_i32 s1, s2, 31
	s_load_dwordx2 s[12:13], s[8:9], 0xe8
	s_lshr_b32 s1, s1, 29
	s_add_i32 s1, s2, s1
	s_and_b32 s3, s1, -8
	s_sub_i32 s4, s2, s3
	s_cmp_gt_i32 s4, 5
	s_cbranch_scc0 .LBB0_1359
	s_mul_i32 s3, s4, 0x2c2
	s_add_i32 s3, s3, 6
	s_cbranch_execz .LBB0_1360
	s_branch .LBB0_1361

;     __device__ __forceinline__ bool next(int i, Unit& u) const {
;         int L = (i / UPT) * G + c;
;         constexpr int n0 = nM0 * nN0, n1 = nM1 * nN1, n2 = nM2 * nN2;
;         if (L < n0) { tile_of(L, nM0, nN0, u.pm, u.pn); u.g = (UPT > 1) ? (i % UPT) : 0; return true; }
; template <class Epi, class Sched>
; __device__ __forceinline__ void gemm_phase(LAS unsigned char* lds, const int K, const Sched& S, const Epi& E) {
;     ...
;     Unit cur, nxt; int ui = 0;
;     if (!S.next(0, cur)) return;
.LBB0_1428:
	s_or_b64 exec, exec, s[8:9]
	s_waitcnt lgkmcnt(0)
	s_barrier
	s_mov_b32 s98, 0
	s_mov_b32 s99, 0
	s_and_b64 vcc, exec, s[6:7]
	v_readfirstlane_b32 s3, v230
	s_cbranch_vccnz .LBB0_1431
	s_ashr_i32 s0, s2, 31
	s_lshr_b32 s0, s0, 29
	s_add_i32 s1, s2, s0
	s_and_b32 s0, s1, -8
	s_sub_i32 s0, s2, s0
	s_cmp_gt_i32 s0, 3
	s_cbranch_scc0 .LBB0_1467
	s_lshl_b32 s4, s0, 7
	s_or_b32 s8, s4, 4
	s_ashr_i32 s1, s1, 3
	s_cbranch_execz .LBB0_1468
	s_branch .LBB0_1469

;     __device__ __forceinline__ bool next(int i, Unit& u) const {
;         int L = (i / UPT) * G + c;
;         constexpr int n0 = nM0 * nN0, n1 = nM1 * nN1, n2 = nM2 * nN2;
;         if (L < n0) { tile_of(L, nM0, nN0, u.pm, u.pn); u.g = (UPT > 1) ? (i % UPT) : 0; return true; }
;         if constexpr (NG > 1) { L -= n0; if (L < n1) { tile_of(L, nM1, nN1, u.pm, u.pn); u.g = 1; return true; }
; template <class Epi, class Sched>
; __device__ __forceinline__ void gemm_phase(LAS unsigned char* lds, const int K, const Sched& S, const Epi& E) {
;     ...
;         cur = nxt; cA = nA; cB = nB; ++ui;
.LBB0_1435:
	s_or_b64 exec, exec, s[14:15]
	s_and_b64 vcc, exec, s[6:7]
	s_mov_b32 s46, s44
	s_mov_b32 s47, s45
	s_mov_b32 s99, s98
	s_mov_b64 s[14:15], s[0:1]
	s_mov_b64 s[12:13], s[10:11]
	s_cbranch_vccnz .LBB0_1464
.LBB0_1436:
	s_add_i32 s29, s29, 1
	s_mul_i32 s0, s29, s68
	s_add_i32 s0, s0, s2
	s_cmpk_lt_i32 s0, 0x42c
	s_cselect_b64 s[10:11], -1, 0
	s_cmpk_gt_i32 s0, 0x42b
	s_cselect_b64 s[6:7], -1, 0
	s_and_b64 vcc, exec, s[6:7]
	s_cbranch_vccnz .LBB0_1442
	s_mov_b32 s98, 0
	s_sub_i32 s100, s0, 0x3e7
	s_and_b32 s101, s100, 0xffffffe7
	s_cmp_eq_u32 s101, 0
	s_cbranch_scc0 .Lrmp8_a
	s_lshr_b32 s100, s100, 3
	s_add_i32 s0, s100, 0x400
	s_branch .Lrmp8_c
.Lrmp8_a:
	s_cmpk_lt_i32 s0, 0x400
	s_cbranch_scc1 .Lrmp8_c
	s_sub_i32 s100, s0, 0x400
	s_lshr_b32 s98, s100, 2
	s_add_i32 s98, s98, 1
	s_and_b32 s100, s100, 3
	s_lshl_b32 s100, s100, 3
	s_add_i32 s0, s100, 0x3e7

;     __device__ __forceinline__ const char* a_of(const Unit& u) const { size_t o = A0; if constexpr (NG > 1 || UPT > 1) o = (u.g == 1) ? A1 : o; if constexpr (NG > 2) o = (u.g == 2) ? A2 : o; return (const char*)ws + o; }
;     __device__ __forceinline__ const char* b_of(const Unit& u) const { size_t o = B0; if constexpr (NG > 1 || UPT > 1) o = (u.g == 1) ? B1 : o; if constexpr (NG > 2) o = (u.g == 2) ? B2 : o; return (const char*)ws + o; }
; template <class Epi, class Sched>
; __device__ __forceinline__ void gemm_phase(LAS unsigned char* lds, const int K, const Sched& S, const Epi& E) {
;     ...
;         const bool has_next = S.next(ui + 1, nxt);
;         const char* nA = has_next ? S.a_of(nxt) + (size_t)nxt.pm * tstep : cA; const char* nB = has_next ? S.b_of(nxt) + (size_t)nxt.pn * tstep : cB;
;     ...
; #pragma unroll
;         for (int a = 0; a < 2; ++a)
; #pragma unroll
;             for (int b = 0; b < 2; ++b)
; #pragma unroll
;                 for (int m = 0; m < 4; ++m)
; #pragma unroll
;                     for (int n = 0; n < 2; ++n) acc[a][b][m][n] = (f32x4){0.f, 0.f, 0.f, 0.f};
.LBB0_1442:
	v_cndmask_b32_e64 v0, 0, 1, s[10:11]
	v_cmp_ne_u32_e64 s[0:1], 1, v0
	s_andn2_b64 vcc, exec, s[10:11]
	s_mov_b64 s[10:11], s[12:13]
	s_cbranch_vccnz .LBB0_1444
	s_mul_i32 s10, s45, 0x160000
	s_mul_hi_i32 s11, s45, 0x160000
	s_add_u32 s10, s24, s10
	s_addc_u32 s11, s25, s11
	s_sub_i32 s100, s98, 1
	s_max_i32 s100, s100, 0
	s_lshl_b32 s100, s100, 9
	s_add_u32 s10, s10, s100
	s_addc_u32 s11, s11, 0
.LBB0_1444:
	s_and_b64 vcc, exec, s[0:1]
	s_mov_b64 s[0:1], s[14:15]
	s_cbranch_vccnz .LBB0_1446
	s_mul_i32 s0, s44, 0x160000
	s_mul_hi_i32 s1, s44, 0x160000
	s_add_u32 s0, s21, s0
	s_addc_u32 s1, s22, s1
	s_sub_i32 s100, s98, 1
	s_max_i32 s100, s100, 0
	s_lshl_b32 s100, s100, 9
	s_add_u32 s0, s0, s100
	s_addc_u32 s1, s1, 0
.LBB0_1446:
	s_add_u32 s48, s14, 0x100
	v_mov_b32_e32 v0, 0
	s_addc_u32 s49, s15, 0
	s_mov_b32 s50, -2
	s_cmp_lg_u32 s99, 0
	s_cselect_b32 s50, 38, s50
	v_mov_b32_e32 v1, v0
	v_mov_b32_e32 v2, v0
	v_mov_b32_e32 v3, v0
	v_mov_b32_e32 v4, v0
	v_mov_b32_e32 v5, v0
	v_mov_b32_e32 v6, v0
	v_mov_b32_e32 v7, v0
	v_mov_b32_e32 v16, v0
	v_mov_b32_e32 v17, v0
	v_mov_b32_e32 v18, v0
	v_mov_b32_e32 v19, v0
	v_mov_b32_e32 v20, v0
	v_mov_b32_e32 v21, v0
	v_mov_b32_e32 v22, v0
	v_mov_b32_e32 v23, v0
	v_mov_b32_e32 v32, v0
	v_mov_b32_e32 v33, v0
	v_mov_b32_e32 v34, v0
	v_mov_b32_e32 v35, v0
	v_mov_b32_e32 v36, v0
	v_mov_b32_e32 v37, v0
	v_mov_b32_e32 v38, v0
	v_mov_b32_e32 v39, v0
	v_mov_b32_e32 v48, v0
	v_mov_b32_e32 v49, v0
	v_mov_b32_e32 v50, v0
	v_mov_b32_e32 v51, v0
	v_mov_b32_e32 v52, v0
	v_mov_b32_e32 v53, v0
	v_mov_b32_e32 v54, v0
	v_mov_b32_e32 v55, v0
	v_mov_b32_e32 v8, v0
	v_mov_b32_e32 v9, v0
	v_mov_b32_e32 v10, v0
	v_mov_b32_e32 v11, v0
	v_mov_b32_e32 v12, v0
	v_mov_b32_e32 v13, v0
	v_mov_b32_e32 v14, v0
	v_mov_b32_e32 v15, v0
	v_mov_b32_e32 v24, v0
	v_mov_b32_e32 v25, v0
	v_mov_b32_e32 v26, v0
	v_mov_b32_e32 v27, v0
	v_mov_b32_e32 v28, v0
	v_mov_b32_e32 v29, v0
	v_mov_b32_e32 v30, v0
	v_mov_b32_e32 v31, v0
	v_mov_b32_e32 v40, v0
	v_mov_b32_e32 v41, v0
	v_mov_b32_e32 v42, v0
	v_mov_b32_e32 v43, v0
	v_mov_b32_e32 v44, v0
	v_mov_b32_e32 v45, v0
	v_mov_b32_e32 v46, v0
	v_mov_b32_e32 v47, v0
	v_mov_b32_e32 v56, v0
	v_mov_b32_e32 v57, v0
	v_mov_b32_e32 v58, v0
	v_mov_b32_e32 v59, v0
	v_mov_b32_e32 v60, v0
	v_mov_b32_e32 v61, v0
	v_mov_b32_e32 v62, v0
	v_mov_b32_e32 v63, v0
	s_waitcnt vmcnt(16)
	v_mov_b32_e32 v64, v0
	v_mov_b32_e32 v65, v0
	v_mov_b32_e32 v66, v0
	v_mov_b32_e32 v67, v0
	v_mov_b32_e32 v68, v0
	v_mov_b32_e32 v69, v0
	v_mov_b32_e32 v70, v0
	v_mov_b32_e32 v71, v0
	v_mov_b32_e32 v80, v0
	v_mov_b32_e32 v81, v0
	v_mov_b32_e32 v82, v0
	v_mov_b32_e32 v83, v0
	v_mov_b32_e32 v84, v0
	v_mov_b32_e32 v85, v0
	v_mov_b32_e32 v86, v0
	v_mov_b32_e32 v87, v0
	v_mov_b32_e32 v96, v0
	v_mov_b32_e32 v97, v0
	v_mov_b32_e32 v98, v0
	v_mov_b32_e32 v99, v0
	v_mov_b32_e32 v100, v0
	v_mov_b32_e32 v101, v0
	v_mov_b32_e32 v102, v0
	v_mov_b32_e32 v103, v0
	v_mov_b32_e32 v112, v0
	v_mov_b32_e32 v113, v0
	v_mov_b32_e32 v114, v0
	v_mov_b32_e32 v115, v0
	v_mov_b32_e32 v116, v0
	v_mov_b32_e32 v117, v0
	v_mov_b32_e32 v118, v0
	v_mov_b32_e32 v119, v0
	v_mov_b32_e32 v72, v0
	v_mov_b32_e32 v73, v0
	v_mov_b32_e32 v74, v0
	v_mov_b32_e32 v75, v0
	v_mov_b32_e32 v76, v0
	v_mov_b32_e32 v77, v0
	v_mov_b32_e32 v78, v0
	v_mov_b32_e32 v79, v0
	v_mov_b32_e32 v88, v0
	v_mov_b32_e32 v89, v0
	v_mov_b32_e32 v90, v0
	v_mov_b32_e32 v91, v0
	v_mov_b32_e32 v92, v0
	v_mov_b32_e32 v93, v0
	v_mov_b32_e32 v94, v0
	v_mov_b32_e32 v95, v0
	v_mov_b32_e32 v104, v0
	v_mov_b32_e32 v105, v0
	v_mov_b32_e32 v106, v0
	v_mov_b32_e32 v107, v0
	v_mov_b32_e32 v108, v0
	v_mov_b32_e32 v109, v0
	v_mov_b32_e32 v110, v0
	v_mov_b32_e32 v111, v0
	v_mov_b32_e32 v120, v0
	v_mov_b32_e32 v121, v0
	v_mov_b32_e32 v122, v0
	v_mov_b32_e32 v123, v0
	v_mov_b32_e32 v124, v0
	v_mov_b32_e32 v125, v0
	v_mov_b32_e32 v126, v0
	v_mov_b32_e32 v127, v0
	s_cmpk_eq_i32 s47, 0x100
	s_cselect_b64 vcc, -1, 0

; __device__ __forceinline__ float bflo(unsigned u) { return __uint_as_float(u << 16); }
; __device__ __forceinline__ float bfhi(unsigned u) { return __uint_as_float(u & 0xffff0000u); }
; #define PG8_STAGE(bufoff, gbase, voff) do { _Pragma("unroll") for (int _i = 0; _i < 2; ++_i) \
;         __builtin_amdgcn_global_load_lds((const unsigned*)((const char*)(gbase) + (voff)[_i]), (LAS unsigned*)(lds + (bufoff) + ldsw + _i * 8192), 16, 0, 0); } while (0)
; #define PG8_MMA(ai, bj, At, Bt) do { __builtin_amdgcn_s_setprio(1); _Pragma("unroll") for (int m = 0; m < 4; ++m) _Pragma("unroll") for (int n = 0; n < 2; ++n) _Pragma("unroll") for (int k = 0; k < 2; ++k) \
;         acc[ai][bj][m][n] = __builtin_amdgcn_mfma_f32_16x16x32_bf16(Bt[n][k], At[m][k], acc[ai][bj][m][n], 0, 0, 0); __builtin_amdgcn_s_setprio(0); } while (0)
; #define PG8_BAR __builtin_amdgcn_s_barrier()
; template <class Epi, class Sched>
; __device__ __forceinline__ void gemm_phase(LAS unsigned char* lds, const int K, const Sched& S, const Epi& E) {
;     ...
;             PG8_BAR; PG8_WAIT_L(0); PG8_MMA(1, 0, At, B0); PG8_BAR; PG8_SCHED;
;             PG8_STAGE(PG8_SB(1, 1), b3 + hstep, voffB);
;             PG8_WAIT_V(6); PG8_BAR; PG8_MMA(1, 1, At, B1); PG8_BAR;
;     __device__ __forceinline__ void operator()(Acc& acc, const Unit& u, int wr, int wc, int fr, int fq) const {
;     ...
;         } else if constexpr (PH == 8) {
;             const bf16_t* X1 = (const bf16_t*)(ws + R_E);
; #pragma unroll
;             for (int ai = 0; ai < 2; ++ai) {
;                 u32x4 xv[4][2];
; #pragma unroll
;                 for (int m = 0; m < 4; ++m)
; #pragma unroll
;                     for (int bj = 0; bj < 2; ++bj) xv[m][bj] = *(const u32x4*)(X1 + (size_t)(row0 + ai * 128 + m * 16) * 1024 + u.pn * 256 + bj * 128 + cl0);
; #pragma unroll
;                 for (int m = 0; m < 4; ++m) { const int R = row0 + ai * 128 + m * 16;
;                     if (R < MP + MS) { float* ys = R < MP ? P.out + O_YP + (size_t)R * 1024 : P.out + O_YS + (size_t)(R - MP) * 1024;
; #pragma unroll
;                         for (int bj = 0; bj < 2; ++bj) { float* y = ys + u.pn * 256 + bj * 128 + cl0; const u32x4 v = xv[m][bj];
;                             *(f32x4*)y = (f32x4){bflo(v.x), bfhi(v.x), bflo(v.y), bfhi(v.y)} + acc[ai][bj][m][0]; *(f32x4*)(y + 4) = (f32x4){bflo(v.z), bfhi(v.z), bflo(v.w), bfhi(v.w)} + acc[ai][bj][m][1]; } } } }
.Lskp8_7:
	s_add_i32 s50, s50, 2
	s_add_u32 s48, s48, 0x100
	s_addc_u32 s49, s49, 0
	s_cmp_gt_u32 s50, 41
	s_mov_b64 s[12:13], s[14:15]
	s_barrier
	s_cbranch_scc0 .LBB0_1447
	s_cmp_lg_u32 s99, 0
	s_cbranch_scc1 .Lp8ks_epi
	v_lshl_add_u32 v170, s47, 8, v163
	s_lshl_b32 s12, s46, 8
	v_or_b32_e32 v180, 16, v170
	s_ashr_i32 s13, s12, 31
	v_ashrrev_i32_e32 v181, 31, v180
	v_lshl_add_u64 v[174:175], s[12:13], 1, v[164:165]
	v_lshlrev_b64 v[128:129], 11, v[180:181]
	v_or_b32_e32 v178, 32, v170
	v_lshl_add_u64 v[128:129], v[174:175], 0, v[128:129]
	v_ashrrev_i32_e32 v179, 31, v178
	global_load_dwordx4 v[148:151], v[128:129], off
	global_load_dwordx4 v[144:147], v[128:129], off offset:256
	v_lshlrev_b64 v[128:129], 11, v[178:179]
	v_or_b32_e32 v176, 48, v170
	v_lshl_add_u64 v[128:129], v[174:175], 0, v[128:129]
	v_ashrrev_i32_e32 v177, 31, v176
	global_load_dwordx4 v[140:143], v[128:129], off
	global_load_dwordx4 v[136:139], v[128:129], off offset:256
	v_lshlrev_b64 v[128:129], 11, v[176:177]
	v_lshl_add_u64 v[128:129], v[174:175], 0, v[128:129]
	global_load_dwordx4 v[132:135], v[128:129], off
	s_nop 0
	global_load_dwordx4 v[128:131], v[128:129], off offset:256
	v_cmp_gt_i32_e32 vcc, s36, v170
	v_lshlrev_b32_e32 v172, 2, v162
	s_and_saveexec_b64 s[14:15], vcc
	s_cbranch_execz .LBB0_1452
	v_ashrrev_i32_e32 v171, 31, v170
	v_lshlrev_b64 v[188:189], 11, v[170:171]
	v_lshl_add_u64 v[192:193], v[174:175], 0, v[188:189]
	global_load_dwordx4 v[188:191], v[192:193], off
	s_nop 0
	global_load_dwordx4 v[192:195], v[192:193], off offset:256
	v_add_u32_e32 v160, 0xffff0000, v170
	v_cmp_gt_i32_e32 vcc, s30, v170
	v_mov_b32_e32 v173, v161
	s_waitcnt vmcnt(0)
	v_lshlrev_b32_e32 v200, 16, v190
	v_cndmask_b32_e32 v197, 0, v171, vcc
	v_cndmask_b32_e32 v196, v160, v170, vcc
	v_cndmask_b32_e64 v160, v186, 0, vcc
	v_lshl_add_u64 v[198:199], s[8:9], 0, v[160:161]
	v_lshlrev_b64 v[196:197], 12, v[196:197]
	v_lshl_add_u64 v[196:197], v[198:199], 0, v[196:197]
	v_lshl_add_u64 v[196:197], s[12:13], 2, v[196:197]
	v_lshlrev_b32_e32 v198, 16, v188
	v_and_b32_e32 v199, 0xffff0000, v188
	v_lshlrev_b32_e32 v188, 16, v189
	v_and_b32_e32 v189, 0xffff0000, v189
	v_lshl_add_u64 v[196:197], v[196:197], 0, v[172:173]
	v_and_b32_e32 v201, 0xffff0000, v190
	v_lshlrev_b32_e32 v190, 16, v191
	v_and_b32_e32 v191, 0xffff0000, v191
	v_lshlrev_b32_e32 v202, 16, v192
	v_and_b32_e32 v203, 0xffff0000, v192
	v_lshlrev_b32_e32 v192, 16, v193
	v_and_b32_e32 v193, 0xffff0000, v193
	v_lshlrev_b32_e32 v204, 16, v194
	v_and_b32_e32 v205, 0xffff0000, v194
	v_lshlrev_b32_e32 v194, 16, v195
	v_and_b32_e32 v195, 0xffff0000, v195
	v_pk_add_f32 v[126:127], v[126:127], v[188:189]
	v_pk_add_f32 v[124:125], v[124:125], v[198:199]
	v_pk_add_f32 v[122:123], v[122:123], v[190:191]
	v_pk_add_f32 v[120:121], v[120:121], v[200:201]
	v_pk_add_f32 v[118:119], v[118:119], v[192:193]
	v_pk_add_f32 v[116:117], v[116:117], v[202:203]
	v_pk_add_f32 v[114:115], v[114:115], v[194:195]
	v_pk_add_f32 v[112:113], v[112:113], v[204:205]
	global_store_dwordx4 v[196:197], v[124:127], off
	global_store_dwordx4 v[196:197], v[120:123], off offset:16
	global_store_dwordx4 v[196:197], v[116:119], off offset:512
	global_store_dwordx4 v[196:197], v[112:115], off offset:528
	s_or_b64 exec, exec, s[14:15]
	v_cmp_gt_i32_e32 vcc, s36, v180
	s_and_saveexec_b64 s[14:15], vcc
	s_cbranch_execnz .LBB0_1453

; __device__ __forceinline__ float bflo(unsigned u) { return __uint_as_float(u << 16); }
; __device__ __forceinline__ float bfhi(unsigned u) { return __uint_as_float(u & 0xffff0000u); }
;     __device__ __forceinline__ void operator()(Acc& acc, const Unit& u, int wr, int wc, int fr, int fq) const {
;     ...
;         } else if constexpr (PH == 8) {
;             const bf16_t* X1 = (const bf16_t*)(ws + R_E);
; #pragma unroll
;             for (int ai = 0; ai < 2; ++ai) {
;                 u32x4 xv[4][2];
; #pragma unroll
;                 for (int m = 0; m < 4; ++m)
; #pragma unroll
;                     for (int bj = 0; bj < 2; ++bj) xv[m][bj] = *(const u32x4*)(X1 + (size_t)(row0 + ai * 128 + m * 16) * 1024 + u.pn * 256 + bj * 128 + cl0);
; #pragma unroll
;                 for (int m = 0; m < 4; ++m) { const int R = row0 + ai * 128 + m * 16;
;                     if (R < MP + MS) { float* ys = R < MP ? P.out + O_YP + (size_t)R * 1024 : P.out + O_YS + (size_t)(R - MP) * 1024;
; #pragma unroll
;                         for (int bj = 0; bj < 2; ++bj) { float* y = ys + u.pn * 256 + bj * 128 + cl0; const u32x4 v = xv[m][bj];
;                             *(f32x4*)y = (f32x4){bflo(v.x), bfhi(v.x), bflo(v.y), bfhi(v.y)} + acc[ai][bj][m][0]; *(f32x4*)(y + 4) = (f32x4){bflo(v.z), bfhi(v.z), bflo(v.w), bfhi(v.w)} + acc[ai][bj][m][1]; } } } }
.Lp8ks_epi:
	s_cmp_eq_u32 s99, 1
	s_cselect_b32 s101, -1, 0
	v_lshl_add_u32 v170, s47, 8, v163
	s_lshl_b32 s12, s46, 8
	v_or_b32_e32 v180, 16, v170
	s_ashr_i32 s13, s12, 31
	v_ashrrev_i32_e32 v181, 31, v180
	v_lshl_add_u64 v[174:175], s[12:13], 1, v[164:165]
	v_lshlrev_b64 v[128:129], 11, v[180:181]
	v_or_b32_e32 v178, 32, v170
	v_lshl_add_u64 v[128:129], v[174:175], 0, v[128:129]
	v_ashrrev_i32_e32 v179, 31, v178
	global_load_dwordx4 v[148:151], v[128:129], off
	global_load_dwordx4 v[144:147], v[128:129], off offset:256
	v_lshlrev_b64 v[128:129], 11, v[178:179]
	v_or_b32_e32 v176, 48, v170
	v_lshl_add_u64 v[128:129], v[174:175], 0, v[128:129]
	v_ashrrev_i32_e32 v177, 31, v176
	global_load_dwordx4 v[140:143], v[128:129], off
	global_load_dwordx4 v[136:139], v[128:129], off offset:256
	v_lshlrev_b64 v[128:129], 11, v[176:177]
	v_lshl_add_u64 v[128:129], v[174:175], 0, v[128:129]
	global_load_dwordx4 v[132:135], v[128:129], off
	s_nop 0
	global_load_dwordx4 v[128:131], v[128:129], off offset:256
	v_cmp_gt_i32_e32 vcc, s36, v170
	v_lshlrev_b32_e32 v172, 2, v162
	s_and_saveexec_b64 s[14:15], vcc
	s_cbranch_execz .Lp8ks_1452
	v_ashrrev_i32_e32 v171, 31, v170
	v_lshlrev_b64 v[188:189], 11, v[170:171]
	v_lshl_add_u64 v[192:193], v[174:175], 0, v[188:189]
	global_load_dwordx4 v[188:191], v[192:193], off
	s_nop 0
	global_load_dwordx4 v[192:195], v[192:193], off offset:256
	v_add_u32_e32 v160, 0xffff0000, v170
	v_cmp_gt_i32_e32 vcc, s30, v170
	v_mov_b32_e32 v173, v161
	s_waitcnt vmcnt(0)
	v_and_b32_e32 v188, s101, v188
	v_and_b32_e32 v189, s101, v189
	v_and_b32_e32 v190, s101, v190
	v_and_b32_e32 v191, s101, v191
	v_and_b32_e32 v192, s101, v192
	v_and_b32_e32 v193, s101, v193
	v_and_b32_e32 v194, s101, v194
	v_and_b32_e32 v195, s101, v195
	v_lshlrev_b32_e32 v200, 16, v190
	v_cndmask_b32_e32 v197, 0, v171, vcc
	v_cndmask_b32_e32 v196, v160, v170, vcc
	v_cndmask_b32_e64 v160, v186, 0, vcc
	v_lshl_add_u64 v[198:199], s[8:9], 0, v[160:161]
	v_lshlrev_b64 v[196:197], 12, v[196:197]
	v_lshl_add_u64 v[196:197], v[198:199], 0, v[196:197]
	v_lshl_add_u64 v[196:197], s[12:13], 2, v[196:197]
	v_lshlrev_b32_e32 v198, 16, v188
	v_and_b32_e32 v199, 0xffff0000, v188
	v_lshlrev_b32_e32 v188, 16, v189
	v_and_b32_e32 v189, 0xffff0000, v189
	v_lshl_add_u64 v[196:197], v[196:197], 0, v[172:173]
	v_and_b32_e32 v201, 0xffff0000, v190
	v_lshlrev_b32_e32 v190, 16, v191
	v_and_b32_e32 v191, 0xffff0000, v191
	v_lshlrev_b32_e32 v202, 16, v192
	v_and_b32_e32 v203, 0xffff0000, v192
	v_lshlrev_b32_e32 v192, 16, v193
	v_and_b32_e32 v193, 0xffff0000, v193
	v_lshlrev_b32_e32 v204, 16, v194
	v_and_b32_e32 v205, 0xffff0000, v194
	v_lshlrev_b32_e32 v194, 16, v195
	v_and_b32_e32 v195, 0xffff0000, v195
	v_pk_add_f32 v[126:127], v[126:127], v[188:189]
	v_pk_add_f32 v[124:125], v[124:125], v[198:199]
	v_pk_add_f32 v[122:123], v[122:123], v[190:191]
	v_pk_add_f32 v[120:121], v[120:121], v[200:201]
	v_pk_add_f32 v[118:119], v[118:119], v[192:193]
	v_pk_add_f32 v[116:117], v[116:117], v[202:203]
	v_pk_add_f32 v[114:115], v[114:115], v[194:195]
	v_pk_add_f32 v[112:113], v[112:113], v[204:205]
	global_atomic_add_f32 v[196:197], v124, off
	global_atomic_add_f32 v[196:197], v125, off offset:4
	global_atomic_add_f32 v[196:197], v126, off offset:8
	global_atomic_add_f32 v[196:197], v127, off offset:12
	global_atomic_add_f32 v[196:197], v120, off offset:16
	global_atomic_add_f32 v[196:197], v121, off offset:20
	global_atomic_add_f32 v[196:197], v122, off offset:24
	global_atomic_add_f32 v[196:197], v123, off offset:28
	global_atomic_add_f32 v[196:197], v116, off offset:512
	global_atomic_add_f32 v[196:197], v117, off offset:516
	global_atomic_add_f32 v[196:197], v118, off offset:520
	global_atomic_add_f32 v[196:197], v119, off offset:524
	global_atomic_add_f32 v[196:197], v112, off offset:528
	global_atomic_add_f32 v[196:197], v113, off offset:532
	global_atomic_add_f32 v[196:197], v114, off offset:536
	global_atomic_add_f32 v[196:197], v115, off offset:540
	s_or_b64 exec, exec, s[14:15]
	v_cmp_gt_i32_e32 vcc, s36, v180
	s_and_saveexec_b64 s[14:15], vcc
	s_cbranch_execnz .Lp8ks_1453

; __device__ __forceinline__ float bflo(unsigned u) { return __uint_as_float(u << 16); }
; __device__ __forceinline__ float bfhi(unsigned u) { return __uint_as_float(u & 0xffff0000u); }
;     __device__ __forceinline__ void operator()(Acc& acc, const Unit& u, int wr, int wc, int fr, int fq) const {
;     ...
;                 for (int m = 0; m < 4; ++m) { const int R = row0 + ai * 128 + m * 16;
;                     if (R < MP + MS) { float* ys = R < MP ? P.out + O_YP + (size_t)R * 1024 : P.out + O_YS + (size_t)(R - MP) * 1024;
; #pragma unroll
;                         for (int bj = 0; bj < 2; ++bj) { float* y = ys + u.pn * 256 + bj * 128 + cl0; const u32x4 v = xv[m][bj];
;                             *(f32x4*)y = (f32x4){bflo(v.x), bfhi(v.x), bflo(v.y), bfhi(v.y)} + acc[ai][bj][m][0]; *(f32x4*)(y + 4) = (f32x4){bflo(v.z), bfhi(v.z), bflo(v.w), bfhi(v.w)} + acc[ai][bj][m][1]; } } } }
.Lp8ks_1451:
	v_add_u32_e32 v96, 0xffff0020, v170
	v_cmp_gt_i32_e32 vcc, s30, v178
	v_mov_b32_e32 v173, v161
	s_waitcnt vmcnt(32)
	v_and_b32_e32 v140, s101, v140
	v_and_b32_e32 v141, s101, v141
	v_and_b32_e32 v142, s101, v142
	v_and_b32_e32 v143, s101, v143
	v_and_b32_e32 v136, s101, v136
	v_and_b32_e32 v137, s101, v137
	v_and_b32_e32 v138, s101, v138
	v_and_b32_e32 v139, s101, v139
	v_lshlrev_b32_e32 v100, 16, v141
	v_cndmask_b32_e32 v97, 0, v179, vcc
	v_cndmask_b32_e32 v96, v96, v178, vcc
	v_cndmask_b32_e64 v160, v186, 0, vcc
	v_lshl_add_u64 v[98:99], s[8:9], 0, v[160:161]
	v_lshlrev_b64 v[96:97], 12, v[96:97]
	v_lshl_add_u64 v[96:97], v[98:99], 0, v[96:97]
	v_lshl_add_u64 v[96:97], s[12:13], 2, v[96:97]
	v_lshlrev_b32_e32 v98, 16, v140
	v_and_b32_e32 v99, 0xffff0000, v140
	v_and_b32_e32 v101, 0xffff0000, v141
	v_lshl_add_u64 v[96:97], v[96:97], 0, v[172:173]
	v_pk_add_f32 v[94:95], v[94:95], v[100:101]
	v_pk_add_f32 v[92:93], v[92:93], v[98:99]
	global_atomic_add_f32 v[96:97], v92, off
	global_atomic_add_f32 v[96:97], v93, off offset:4
	global_atomic_add_f32 v[96:97], v94, off offset:8
	global_atomic_add_f32 v[96:97], v95, off offset:12
	s_nop 1
	v_lshlrev_b32_e32 v92, 16, v142
	v_and_b32_e32 v93, 0xffff0000, v142
	v_lshlrev_b32_e32 v94, 16, v143
	v_and_b32_e32 v95, 0xffff0000, v143
	v_pk_add_f32 v[90:91], v[90:91], v[94:95]
	v_pk_add_f32 v[88:89], v[88:89], v[92:93]
	global_atomic_add_f32 v[96:97], v88, off offset:16
	global_atomic_add_f32 v[96:97], v89, off offset:20
	global_atomic_add_f32 v[96:97], v90, off offset:24
	global_atomic_add_f32 v[96:97], v91, off offset:28
	s_nop 1
	v_lshlrev_b32_e32 v88, 16, v136
	v_and_b32_e32 v89, 0xffff0000, v136
	v_lshlrev_b32_e32 v90, 16, v137
	v_and_b32_e32 v91, 0xffff0000, v137
	v_pk_add_f32 v[86:87], v[86:87], v[90:91]
	v_pk_add_f32 v[84:85], v[84:85], v[88:89]
	global_atomic_add_f32 v[96:97], v84, off offset:512
	global_atomic_add_f32 v[96:97], v85, off offset:516
	global_atomic_add_f32 v[96:97], v86, off offset:520
	global_atomic_add_f32 v[96:97], v87, off offset:524
	s_nop 1
	v_lshlrev_b32_e32 v84, 16, v138
	v_and_b32_e32 v85, 0xffff0000, v138
	v_lshlrev_b32_e32 v86, 16, v139
	v_and_b32_e32 v87, 0xffff0000, v139
	v_pk_add_f32 v[82:83], v[82:83], v[86:87]
	v_pk_add_f32 v[80:81], v[80:81], v[84:85]
	global_atomic_add_f32 v[96:97], v80, off offset:528
	global_atomic_add_f32 v[96:97], v81, off offset:532
	global_atomic_add_f32 v[96:97], v82, off offset:536
	global_atomic_add_f32 v[96:97], v83, off offset:540
	s_or_b64 exec, exec, s[14:15]
	v_cmp_gt_i32_e32 vcc, s36, v176
	s_and_saveexec_b64 s[14:15], vcc
	s_cbranch_execnz .Lp8ks_1455
	s_branch .Lp8ks_1456

; __device__ __forceinline__ float bflo(unsigned u) { return __uint_as_float(u << 16); }
; __device__ __forceinline__ float bfhi(unsigned u) { return __uint_as_float(u & 0xffff0000u); }
;     __device__ __forceinline__ void operator()(Acc& acc, const Unit& u, int wr, int wc, int fr, int fq) const {
;     ...
;                 for (int m = 0; m < 4; ++m) { const int R = row0 + ai * 128 + m * 16;
;                     if (R < MP + MS) { float* ys = R < MP ? P.out + O_YP + (size_t)R * 1024 : P.out + O_YS + (size_t)(R - MP) * 1024;
; #pragma unroll
;                         for (int bj = 0; bj < 2; ++bj) { float* y = ys + u.pn * 256 + bj * 128 + cl0; const u32x4 v = xv[m][bj];
;                             *(f32x4*)y = (f32x4){bflo(v.x), bfhi(v.x), bflo(v.y), bfhi(v.y)} + acc[ai][bj][m][0]; *(f32x4*)(y + 4) = (f32x4){bflo(v.z), bfhi(v.z), bflo(v.w), bfhi(v.w)} + acc[ai][bj][m][1]; } } } }
.Lp8ks_1453:
	v_add_u32_e32 v112, 0xffff0010, v170
	v_cmp_gt_i32_e32 vcc, s30, v180
	v_mov_b32_e32 v173, v161
	s_waitcnt vmcnt(16)
	v_and_b32_e32 v148, s101, v148
	v_and_b32_e32 v149, s101, v149
	v_and_b32_e32 v150, s101, v150
	v_and_b32_e32 v151, s101, v151
	v_and_b32_e32 v144, s101, v144
	v_and_b32_e32 v145, s101, v145
	v_and_b32_e32 v146, s101, v146
	v_and_b32_e32 v147, s101, v147
	v_lshlrev_b32_e32 v116, 16, v149
	v_cndmask_b32_e32 v113, 0, v181, vcc
	v_cndmask_b32_e32 v112, v112, v180, vcc
	v_cndmask_b32_e64 v160, v186, 0, vcc
	v_lshl_add_u64 v[114:115], s[8:9], 0, v[160:161]
	v_lshlrev_b64 v[112:113], 12, v[112:113]
	v_lshl_add_u64 v[112:113], v[114:115], 0, v[112:113]
	v_lshl_add_u64 v[112:113], s[12:13], 2, v[112:113]
	v_lshlrev_b32_e32 v114, 16, v148
	v_and_b32_e32 v115, 0xffff0000, v148
	v_and_b32_e32 v117, 0xffff0000, v149
	v_lshl_add_u64 v[112:113], v[112:113], 0, v[172:173]
	v_pk_add_f32 v[110:111], v[110:111], v[116:117]
	v_pk_add_f32 v[108:109], v[108:109], v[114:115]
	global_atomic_add_f32 v[112:113], v108, off
	global_atomic_add_f32 v[112:113], v109, off offset:4
	global_atomic_add_f32 v[112:113], v110, off offset:8
	global_atomic_add_f32 v[112:113], v111, off offset:12
	s_nop 1
	v_lshlrev_b32_e32 v108, 16, v150
	v_and_b32_e32 v109, 0xffff0000, v150
	v_lshlrev_b32_e32 v110, 16, v151
	v_and_b32_e32 v111, 0xffff0000, v151
	v_pk_add_f32 v[106:107], v[106:107], v[110:111]
	v_pk_add_f32 v[104:105], v[104:105], v[108:109]
	global_atomic_add_f32 v[112:113], v104, off offset:16
	global_atomic_add_f32 v[112:113], v105, off offset:20
	global_atomic_add_f32 v[112:113], v106, off offset:24
	global_atomic_add_f32 v[112:113], v107, off offset:28
	s_nop 1
	v_lshlrev_b32_e32 v104, 16, v144
	v_and_b32_e32 v105, 0xffff0000, v144
	v_lshlrev_b32_e32 v106, 16, v145
	v_and_b32_e32 v107, 0xffff0000, v145
	v_pk_add_f32 v[102:103], v[102:103], v[106:107]
	v_pk_add_f32 v[100:101], v[100:101], v[104:105]
	global_atomic_add_f32 v[112:113], v100, off offset:512
	global_atomic_add_f32 v[112:113], v101, off offset:516
	global_atomic_add_f32 v[112:113], v102, off offset:520
	global_atomic_add_f32 v[112:113], v103, off offset:524
	s_nop 1
	v_lshlrev_b32_e32 v100, 16, v146
	v_and_b32_e32 v101, 0xffff0000, v146
	v_lshlrev_b32_e32 v102, 16, v147
	v_and_b32_e32 v103, 0xffff0000, v147
	v_pk_add_f32 v[98:99], v[98:99], v[102:103]
	v_pk_add_f32 v[96:97], v[96:97], v[100:101]
	global_atomic_add_f32 v[112:113], v96, off offset:528
	global_atomic_add_f32 v[112:113], v97, off offset:532
	global_atomic_add_f32 v[112:113], v98, off offset:536
	global_atomic_add_f32 v[112:113], v99, off offset:540
	s_or_b64 exec, exec, s[14:15]
	v_cmp_gt_i32_e32 vcc, s36, v178
	s_and_saveexec_b64 s[14:15], vcc
	s_cbranch_execnz .Lp8ks_1451

; __device__ __forceinline__ float bflo(unsigned u) { return __uint_as_float(u << 16); }
; __device__ __forceinline__ float bfhi(unsigned u) { return __uint_as_float(u & 0xffff0000u); }
;     __device__ __forceinline__ void operator()(Acc& acc, const Unit& u, int wr, int wc, int fr, int fq) const {
;     ...
;                 for (int m = 0; m < 4; ++m) { const int R = row0 + ai * 128 + m * 16;
;                     if (R < MP + MS) { float* ys = R < MP ? P.out + O_YP + (size_t)R * 1024 : P.out + O_YS + (size_t)(R - MP) * 1024;
; #pragma unroll
;                         for (int bj = 0; bj < 2; ++bj) { float* y = ys + u.pn * 256 + bj * 128 + cl0; const u32x4 v = xv[m][bj];
;                             *(f32x4*)y = (f32x4){bflo(v.x), bfhi(v.x), bflo(v.y), bfhi(v.y)} + acc[ai][bj][m][0]; *(f32x4*)(y + 4) = (f32x4){bflo(v.z), bfhi(v.z), bflo(v.w), bfhi(v.w)} + acc[ai][bj][m][1]; } } } }
.Lp8ks_1455:
	v_add_u32_e32 v80, 0xffff0030, v170
	v_cmp_gt_i32_e32 vcc, s30, v176
	v_mov_b32_e32 v173, v161
	s_waitcnt vmcnt(48)
	v_and_b32_e32 v132, s101, v132
	v_and_b32_e32 v133, s101, v133
	v_and_b32_e32 v134, s101, v134
	v_and_b32_e32 v135, s101, v135
	v_and_b32_e32 v128, s101, v128
	v_and_b32_e32 v129, s101, v129
	v_and_b32_e32 v130, s101, v130
	v_and_b32_e32 v131, s101, v131
	v_lshlrev_b32_e32 v84, 16, v133
	v_cndmask_b32_e32 v81, 0, v177, vcc
	v_cndmask_b32_e32 v80, v80, v176, vcc
	v_cndmask_b32_e64 v160, v186, 0, vcc
	v_lshl_add_u64 v[82:83], s[8:9], 0, v[160:161]
	v_lshlrev_b64 v[80:81], 12, v[80:81]
	v_lshl_add_u64 v[80:81], v[82:83], 0, v[80:81]
	v_lshl_add_u64 v[80:81], s[12:13], 2, v[80:81]
	v_lshlrev_b32_e32 v82, 16, v132
	v_and_b32_e32 v83, 0xffff0000, v132
	v_and_b32_e32 v85, 0xffff0000, v133
	v_lshl_add_u64 v[80:81], v[80:81], 0, v[172:173]
	v_pk_add_f32 v[78:79], v[78:79], v[84:85]
	v_pk_add_f32 v[76:77], v[76:77], v[82:83]
	global_atomic_add_f32 v[80:81], v76, off
	global_atomic_add_f32 v[80:81], v77, off offset:4
	global_atomic_add_f32 v[80:81], v78, off offset:8
	global_atomic_add_f32 v[80:81], v79, off offset:12
	s_nop 1
	v_lshlrev_b32_e32 v76, 16, v134
	v_and_b32_e32 v77, 0xffff0000, v134
	v_lshlrev_b32_e32 v78, 16, v135
	v_and_b32_e32 v79, 0xffff0000, v135
	v_pk_add_f32 v[74:75], v[74:75], v[78:79]
	v_pk_add_f32 v[72:73], v[72:73], v[76:77]
	global_atomic_add_f32 v[80:81], v72, off offset:16
	global_atomic_add_f32 v[80:81], v73, off offset:20
	global_atomic_add_f32 v[80:81], v74, off offset:24
	global_atomic_add_f32 v[80:81], v75, off offset:28
	s_nop 1
	v_lshlrev_b32_e32 v72, 16, v128
	v_and_b32_e32 v73, 0xffff0000, v128
	v_lshlrev_b32_e32 v74, 16, v129
	v_and_b32_e32 v75, 0xffff0000, v129
	v_pk_add_f32 v[70:71], v[70:71], v[74:75]
	v_pk_add_f32 v[68:69], v[68:69], v[72:73]
	global_atomic_add_f32 v[80:81], v68, off offset:512
	global_atomic_add_f32 v[80:81], v69, off offset:516
	global_atomic_add_f32 v[80:81], v70, off offset:520
	global_atomic_add_f32 v[80:81], v71, off offset:524
	s_nop 1
	v_lshlrev_b32_e32 v68, 16, v130
	v_and_b32_e32 v69, 0xffff0000, v130
	v_lshlrev_b32_e32 v70, 16, v131
	v_and_b32_e32 v71, 0xffff0000, v131
	v_pk_add_f32 v[66:67], v[66:67], v[70:71]
	v_pk_add_f32 v[64:65], v[64:65], v[68:69]
	global_atomic_add_f32 v[80:81], v64, off offset:528
	global_atomic_add_f32 v[80:81], v65, off offset:532
	global_atomic_add_f32 v[80:81], v66, off offset:536
	global_atomic_add_f32 v[80:81], v67, off offset:540
.Lp8ks_1456:
	s_or_b64 exec, exec, s[14:15]
	s_branch .LBB0_1435
